# v54 + prologue x-row loop: 4 rows' 32 loads issued up front with counted vmcnt (was 1 load per wait), interleaved wave sums
# baseline (speedup 1.0000x reference)
.LBB0_452:
	s_cmpk_gt_i32 s2, 0x1fff
	s_cbranch_scc1 .LBB0_457
	s_ashr_i32 s3, s2, 31
	s_load_dwordx2 s[0:1], s[30:31], 0x0
	v_cmp_lt_i32_e32 vcc, v239, v238
	s_lshl_b64 s[8:9], s[2:3], 7
	v_and_b32_e32 v0, 63, v9
	v_cndmask_b32_e32 v1, v237, v239, vcc
	v_cmp_lt_i32_e32 vcc, v240, v238
	s_add_u32 s8, s8, 0x100000
	v_lshlrev_b32_e32 v40, 2, v1
	v_cndmask_b32_e32 v1, v237, v240, vcc
	v_cmp_lt_i32_e32 vcc, v241, v238
	s_addc_u32 s9, s9, 0
	v_lshlrev_b32_e32 v204, 2, v0
	v_lshlrev_b32_e32 v41, 2, v1
	v_cndmask_b32_e32 v1, v237, v241, vcc
	v_cmp_lt_i32_e32 vcc, v208, v238
	v_lshl_add_u64 v[32:33], s[8:9], 0, v[204:205]
	s_lshl_b64 s[8:9], s[2:3], 12
	v_lshlrev_b32_e32 v42, 2, v1
	v_cndmask_b32_e32 v1, v237, v208, vcc
	v_cmp_lt_i32_e32 vcc, v243, v238
	v_lshl_or_b32 v34, v0, 3, s8
	v_mov_b32_e32 v35, s9
	s_lshl_b64 s[8:9], s[2:3], 13
	v_lshlrev_b32_e32 v43, 2, v1
	v_cndmask_b32_e32 v1, v237, v243, vcc
	v_cmp_lt_i32_e32 vcc, v244, v238
	s_waitcnt lgkmcnt(0)
	s_add_u32 s0, s0, s8
	v_lshlrev_b32_e32 v44, 2, v1
	v_cndmask_b32_e32 v1, v237, v244, vcc
	v_lshlrev_b32_e32 v204, 4, v0
	s_addc_u32 s1, s1, s9
	v_lshlrev_b32_e32 v45, 2, v1
	v_cmp_gt_u32_e64 s[4:5], 32, v0
	v_cmp_eq_u32_e64 s[6:7], 0, v0
	v_lshl_add_u64 v[0:1], s[0:1], 0, v[204:205]
	s_mov_b64 s[0:1], 0x1c00
	v_readlane_b32 s10, v209, 16
	v_readlane_b32 s14, v209, 18
	v_readlane_b32 s16, v209, 20
	v_lshl_add_u64 v[36:37], v[0:1], 0, s[0:1]
	v_readlane_b32 s11, v209, 17
	v_readlane_b32 s15, v209, 19
	v_readlane_b32 s17, v209, 21
	s_mul_i32 s0, s24, 3
	s_add_i32 s0, s0, s2
	s_cmpk_gt_i32 s0, 0x1fff
	s_cbranch_scc1 .Lx_slow
	s_add_i32 s0, s0, s24
	s_cmpk_gt_i32 s0, 0x1fff
	s_cbranch_scc1 .Lx_fast

.Lx_fast:
	v_add_co_u32_e32 v48, vcc, 0xfffff400, v36
	s_nop 1
	v_addc_co_u32_e32 v49, vcc, -1, v37, vcc
	v_lshl_add_u64 v[50:51], v[48:49], 0, s[16:17]
	v_lshl_add_u64 v[52:53], v[50:51], 0, s[16:17]
	v_lshl_add_u64 v[54:55], v[52:53], 0, s[16:17]
	global_load_dwordx4 v[64:67], v[48:49], off offset:-4096
	global_load_dwordx4 v[68:71], v[48:49], off offset:-3072
	global_load_dwordx4 v[72:75], v[48:49], off offset:-2048
	global_load_dwordx4 v[76:79], v[48:49], off offset:-1024
	global_load_dwordx4 v[80:83], v[48:49], off
	global_load_dwordx4 v[84:87], v[48:49], off offset:1024
	global_load_dwordx4 v[88:91], v[48:49], off offset:2048
	global_load_dwordx4 v[92:95], v[48:49], off offset:3072
	global_load_dwordx4 v[96:99], v[50:51], off offset:-4096
	global_load_dwordx4 v[100:103], v[50:51], off offset:-3072
	global_load_dwordx4 v[104:107], v[50:51], off offset:-2048
	global_load_dwordx4 v[108:111], v[50:51], off offset:-1024
	global_load_dwordx4 v[112:115], v[50:51], off
	global_load_dwordx4 v[116:119], v[50:51], off offset:1024
	global_load_dwordx4 v[120:123], v[50:51], off offset:2048
	global_load_dwordx4 v[124:127], v[50:51], off offset:3072
	global_load_dwordx4 v[128:131], v[52:53], off offset:-4096
	global_load_dwordx4 v[132:135], v[52:53], off offset:-3072
	global_load_dwordx4 v[136:139], v[52:53], off offset:-2048
	global_load_dwordx4 v[140:143], v[52:53], off offset:-1024
	global_load_dwordx4 v[144:147], v[52:53], off
	global_load_dwordx4 v[148:151], v[52:53], off offset:1024
	global_load_dwordx4 v[152:155], v[52:53], off offset:2048
	global_load_dwordx4 v[156:159], v[52:53], off offset:3072
	global_load_dwordx4 v[160:163], v[54:55], off offset:-4096
	global_load_dwordx4 v[164:167], v[54:55], off offset:-3072
	global_load_dwordx4 v[168:171], v[54:55], off offset:-2048
	global_load_dwordx4 v[172:175], v[54:55], off offset:-1024
	global_load_dwordx4 v[176:179], v[54:55], off
	global_load_dwordx4 v[180:183], v[54:55], off offset:1024
	global_load_dwordx4 v[184:187], v[54:55], off offset:2048
	global_load_dwordx4 v[188:191], v[54:55], off offset:3072
	s_mov_b32 s0, 0x15e00000
	v_lshl_add_u64 v[56:57], s[18:19], 0, v[34:35]
	v_add_co_u32_e32 v56, vcc, s0, v56
	s_nop 1
	v_addc_co_u32_e32 v57, vcc, 0, v57, vcc
	v_lshl_add_u64 v[58:59], v[56:57], 0, s[14:15]
	v_lshl_add_u64 v[60:61], v[58:59], 0, s[14:15]
	v_lshl_add_u64 v[62:63], v[60:61], 0, s[14:15]
	v_lshl_add_u64 v[192:193], s[18:19], 0, v[32:33]
	v_lshl_add_u64 v[194:195], v[192:193], 0, s[10:11]
	v_lshl_add_u64 v[196:197], v[194:195], 0, s[10:11]
	v_lshl_add_u64 v[198:199], v[196:197], 0, s[10:11]
	s_waitcnt vmcnt(24)
	v_mul_f32_e32 v0, v65, v65
	v_mul_f32_e32 v1, v67, v67
	v_fmac_f32_e32 v0, v64, v64
	v_fmac_f32_e32 v1, v66, v66
	v_add_f32_e32 v2, v0, v1
	v_mul_f32_e32 v3, v69, v69
	v_mul_f32_e32 v4, v71, v71
	v_fmac_f32_e32 v3, v68, v68
	v_fmac_f32_e32 v4, v70, v70
	v_add_f32_e32 v5, v3, v4
	v_add_f32_e32 v8, v2, v5
	v_mul_f32_e32 v0, v73, v73
	v_mul_f32_e32 v1, v75, v75
	v_fmac_f32_e32 v0, v72, v72
	v_fmac_f32_e32 v1, v74, v74
	v_add_f32_e32 v2, v0, v1
	v_add_f32_e32 v8, v8, v2
	v_mul_f32_e32 v3, v77, v77
	v_mul_f32_e32 v4, v79, v79
	v_fmac_f32_e32 v3, v76, v76
	v_fmac_f32_e32 v4, v78, v78
	v_add_f32_e32 v5, v3, v4
	v_add_f32_e32 v8, v8, v5
	v_mul_f32_e32 v0, v81, v81
	v_mul_f32_e32 v1, v83, v83
	v_fmac_f32_e32 v0, v80, v80
	v_fmac_f32_e32 v1, v82, v82
	v_add_f32_e32 v2, v0, v1
	v_add_f32_e32 v8, v8, v2
	v_mul_f32_e32 v3, v85, v85
	v_mul_f32_e32 v4, v87, v87
	v_fmac_f32_e32 v3, v84, v84
	v_fmac_f32_e32 v4, v86, v86
	v_add_f32_e32 v5, v3, v4
	v_add_f32_e32 v8, v8, v5
	v_mul_f32_e32 v0, v89, v89
	v_mul_f32_e32 v1, v91, v91
	v_fmac_f32_e32 v0, v88, v88
	v_fmac_f32_e32 v1, v90, v90
	v_add_f32_e32 v2, v0, v1
	v_add_f32_e32 v8, v8, v2
	v_mul_f32_e32 v3, v93, v93
	v_mul_f32_e32 v4, v95, v95
	v_fmac_f32_e32 v3, v92, v92
	v_fmac_f32_e32 v4, v94, v94
	v_add_f32_e32 v5, v3, v4
	v_add_f32_e32 v8, v8, v5
	v_cvt_pk_bf16_f32 v64, v64, v65
	v_cvt_pk_bf16_f32 v65, v66, v67
	global_store_dwordx2 v[56:57], v[64:65], off
	v_cvt_pk_bf16_f32 v68, v68, v69
	v_cvt_pk_bf16_f32 v69, v70, v71
	global_store_dwordx2 v[56:57], v[68:69], off offset:512
	v_cvt_pk_bf16_f32 v72, v72, v73
	v_cvt_pk_bf16_f32 v73, v74, v75
	global_store_dwordx2 v[56:57], v[72:73], off offset:1024
	v_cvt_pk_bf16_f32 v76, v76, v77
	v_cvt_pk_bf16_f32 v77, v78, v79
	global_store_dwordx2 v[56:57], v[76:77], off offset:1536
	v_cvt_pk_bf16_f32 v80, v80, v81
	v_cvt_pk_bf16_f32 v81, v82, v83
	global_store_dwordx2 v[56:57], v[80:81], off offset:2048
	v_cvt_pk_bf16_f32 v84, v84, v85
	v_cvt_pk_bf16_f32 v85, v86, v87
	global_store_dwordx2 v[56:57], v[84:85], off offset:2560
	v_cvt_pk_bf16_f32 v88, v88, v89
	v_cvt_pk_bf16_f32 v89, v90, v91
	global_store_dwordx2 v[56:57], v[88:89], off offset:3072
	v_cvt_pk_bf16_f32 v92, v92, v93
	v_cvt_pk_bf16_f32 v93, v94, v95
	global_store_dwordx2 v[56:57], v[92:93], off offset:3584
	s_waitcnt vmcnt(24)
	v_mul_f32_e32 v0, v97, v97
	v_mul_f32_e32 v1, v99, v99
	v_fmac_f32_e32 v0, v96, v96
	v_fmac_f32_e32 v1, v98, v98
	v_add_f32_e32 v2, v0, v1
	v_mul_f32_e32 v3, v101, v101
	v_mul_f32_e32 v4, v103, v103
	v_fmac_f32_e32 v3, v100, v100
	v_fmac_f32_e32 v4, v102, v102
	v_add_f32_e32 v5, v3, v4
	v_add_f32_e32 v9, v2, v5
	v_mul_f32_e32 v0, v105, v105
	v_mul_f32_e32 v1, v107, v107
	v_fmac_f32_e32 v0, v104, v104
	v_fmac_f32_e32 v1, v106, v106
	v_add_f32_e32 v2, v0, v1
	v_add_f32_e32 v9, v9, v2
	v_mul_f32_e32 v3, v109, v109
	v_mul_f32_e32 v4, v111, v111
	v_fmac_f32_e32 v3, v108, v108
	v_fmac_f32_e32 v4, v110, v110
	v_add_f32_e32 v5, v3, v4
	v_add_f32_e32 v9, v9, v5
	v_mul_f32_e32 v0, v113, v113
	v_mul_f32_e32 v1, v115, v115
	v_fmac_f32_e32 v0, v112, v112
	v_fmac_f32_e32 v1, v114, v114
	v_add_f32_e32 v2, v0, v1
	v_add_f32_e32 v9, v9, v2
	v_mul_f32_e32 v3, v117, v117
	v_mul_f32_e32 v4, v119, v119
	v_fmac_f32_e32 v3, v116, v116
	v_fmac_f32_e32 v4, v118, v118
	v_add_f32_e32 v5, v3, v4
	v_add_f32_e32 v9, v9, v5
	v_mul_f32_e32 v0, v121, v121
	v_mul_f32_e32 v1, v123, v123
	v_fmac_f32_e32 v0, v120, v120
	v_fmac_f32_e32 v1, v122, v122
	v_add_f32_e32 v2, v0, v1
	v_add_f32_e32 v9, v9, v2
	v_mul_f32_e32 v3, v125, v125
	v_mul_f32_e32 v4, v127, v127
	v_fmac_f32_e32 v3, v124, v124
	v_fmac_f32_e32 v4, v126, v126
	v_add_f32_e32 v5, v3, v4
	v_add_f32_e32 v9, v9, v5
	v_cvt_pk_bf16_f32 v96, v96, v97
	v_cvt_pk_bf16_f32 v97, v98, v99
	global_store_dwordx2 v[58:59], v[96:97], off
	v_cvt_pk_bf16_f32 v100, v100, v101
	v_cvt_pk_bf16_f32 v101, v102, v103
	global_store_dwordx2 v[58:59], v[100:101], off offset:512
	v_cvt_pk_bf16_f32 v104, v104, v105
	v_cvt_pk_bf16_f32 v105, v106, v107
	global_store_dwordx2 v[58:59], v[104:105], off offset:1024
	v_cvt_pk_bf16_f32 v108, v108, v109
	v_cvt_pk_bf16_f32 v109, v110, v111
	global_store_dwordx2 v[58:59], v[108:109], off offset:1536
	v_cvt_pk_bf16_f32 v112, v112, v113
	v_cvt_pk_bf16_f32 v113, v114, v115
	global_store_dwordx2 v[58:59], v[112:113], off offset:2048
	v_cvt_pk_bf16_f32 v116, v116, v117
	v_cvt_pk_bf16_f32 v117, v118, v119
	global_store_dwordx2 v[58:59], v[116:117], off offset:2560
	v_cvt_pk_bf16_f32 v120, v120, v121
	v_cvt_pk_bf16_f32 v121, v122, v123
	global_store_dwordx2 v[58:59], v[120:121], off offset:3072
	v_cvt_pk_bf16_f32 v124, v124, v125
	v_cvt_pk_bf16_f32 v125, v126, v127
	global_store_dwordx2 v[58:59], v[124:125], off offset:3584
	s_waitcnt vmcnt(24)
	v_mul_f32_e32 v0, v129, v129
	v_mul_f32_e32 v1, v131, v131
	v_fmac_f32_e32 v0, v128, v128
	v_fmac_f32_e32 v1, v130, v130
	v_add_f32_e32 v2, v0, v1
	v_mul_f32_e32 v3, v133, v133
	v_mul_f32_e32 v4, v135, v135
	v_fmac_f32_e32 v3, v132, v132
	v_fmac_f32_e32 v4, v134, v134
	v_add_f32_e32 v5, v3, v4
	v_add_f32_e32 v10, v2, v5
	v_mul_f32_e32 v0, v137, v137
	v_mul_f32_e32 v1, v139, v139
	v_fmac_f32_e32 v0, v136, v136
	v_fmac_f32_e32 v1, v138, v138
	v_add_f32_e32 v2, v0, v1
	v_add_f32_e32 v10, v10, v2
	v_mul_f32_e32 v3, v141, v141
	v_mul_f32_e32 v4, v143, v143
	v_fmac_f32_e32 v3, v140, v140
	v_fmac_f32_e32 v4, v142, v142
	v_add_f32_e32 v5, v3, v4
	v_add_f32_e32 v10, v10, v5
	v_mul_f32_e32 v0, v145, v145
	v_mul_f32_e32 v1, v147, v147
	v_fmac_f32_e32 v0, v144, v144
	v_fmac_f32_e32 v1, v146, v146
	v_add_f32_e32 v2, v0, v1
	v_add_f32_e32 v10, v10, v2
	v_mul_f32_e32 v3, v149, v149
	v_mul_f32_e32 v4, v151, v151
	v_fmac_f32_e32 v3, v148, v148
	v_fmac_f32_e32 v4, v150, v150
	v_add_f32_e32 v5, v3, v4
	v_add_f32_e32 v10, v10, v5
	v_mul_f32_e32 v0, v153, v153
	v_mul_f32_e32 v1, v155, v155
	v_fmac_f32_e32 v0, v152, v152
	v_fmac_f32_e32 v1, v154, v154
	v_add_f32_e32 v2, v0, v1
	v_add_f32_e32 v10, v10, v2
	v_mul_f32_e32 v3, v157, v157
	v_mul_f32_e32 v4, v159, v159
	v_fmac_f32_e32 v3, v156, v156
	v_fmac_f32_e32 v4, v158, v158
	v_add_f32_e32 v5, v3, v4
	v_add_f32_e32 v10, v10, v5
	v_cvt_pk_bf16_f32 v128, v128, v129
	v_cvt_pk_bf16_f32 v129, v130, v131
	global_store_dwordx2 v[60:61], v[128:129], off
	v_cvt_pk_bf16_f32 v132, v132, v133
	v_cvt_pk_bf16_f32 v133, v134, v135
	global_store_dwordx2 v[60:61], v[132:133], off offset:512
	v_cvt_pk_bf16_f32 v136, v136, v137
	v_cvt_pk_bf16_f32 v137, v138, v139
	global_store_dwordx2 v[60:61], v[136:137], off offset:1024
	v_cvt_pk_bf16_f32 v140, v140, v141
	v_cvt_pk_bf16_f32 v141, v142, v143
	global_store_dwordx2 v[60:61], v[140:141], off offset:1536
	v_cvt_pk_bf16_f32 v144, v144, v145
	v_cvt_pk_bf16_f32 v145, v146, v147
	global_store_dwordx2 v[60:61], v[144:145], off offset:2048
	v_cvt_pk_bf16_f32 v148, v148, v149
	v_cvt_pk_bf16_f32 v149, v150, v151
	global_store_dwordx2 v[60:61], v[148:149], off offset:2560
	v_cvt_pk_bf16_f32 v152, v152, v153
	v_cvt_pk_bf16_f32 v153, v154, v155
	global_store_dwordx2 v[60:61], v[152:153], off offset:3072
	v_cvt_pk_bf16_f32 v156, v156, v157
	v_cvt_pk_bf16_f32 v157, v158, v159
	global_store_dwordx2 v[60:61], v[156:157], off offset:3584
	s_waitcnt vmcnt(24)
	v_mul_f32_e32 v0, v161, v161
	v_mul_f32_e32 v1, v163, v163
	v_fmac_f32_e32 v0, v160, v160
	v_fmac_f32_e32 v1, v162, v162
	v_add_f32_e32 v2, v0, v1
	v_mul_f32_e32 v3, v165, v165
	v_mul_f32_e32 v4, v167, v167
	v_fmac_f32_e32 v3, v164, v164
	v_fmac_f32_e32 v4, v166, v166
	v_add_f32_e32 v5, v3, v4
	v_add_f32_e32 v11, v2, v5
	v_mul_f32_e32 v0, v169, v169
	v_mul_f32_e32 v1, v171, v171
	v_fmac_f32_e32 v0, v168, v168
	v_fmac_f32_e32 v1, v170, v170
	v_add_f32_e32 v2, v0, v1
	v_add_f32_e32 v11, v11, v2
	v_mul_f32_e32 v3, v173, v173
	v_mul_f32_e32 v4, v175, v175
	v_fmac_f32_e32 v3, v172, v172
	v_fmac_f32_e32 v4, v174, v174
	v_add_f32_e32 v5, v3, v4
	v_add_f32_e32 v11, v11, v5
	v_mul_f32_e32 v0, v177, v177
	v_mul_f32_e32 v1, v179, v179
	v_fmac_f32_e32 v0, v176, v176
	v_fmac_f32_e32 v1, v178, v178
	v_add_f32_e32 v2, v0, v1
	v_add_f32_e32 v11, v11, v2
	v_mul_f32_e32 v3, v181, v181
	v_mul_f32_e32 v4, v183, v183
	v_fmac_f32_e32 v3, v180, v180
	v_fmac_f32_e32 v4, v182, v182
	v_add_f32_e32 v5, v3, v4
	v_add_f32_e32 v11, v11, v5
	v_mul_f32_e32 v0, v185, v185
	v_mul_f32_e32 v1, v187, v187
	v_fmac_f32_e32 v0, v184, v184
	v_fmac_f32_e32 v1, v186, v186
	v_add_f32_e32 v2, v0, v1
	v_add_f32_e32 v11, v11, v2
	v_mul_f32_e32 v3, v189, v189
	v_mul_f32_e32 v4, v191, v191
	v_fmac_f32_e32 v3, v188, v188
	v_fmac_f32_e32 v4, v190, v190
	v_add_f32_e32 v5, v3, v4
	v_add_f32_e32 v11, v11, v5
	v_cvt_pk_bf16_f32 v160, v160, v161
	v_cvt_pk_bf16_f32 v161, v162, v163
	global_store_dwordx2 v[62:63], v[160:161], off
	v_cvt_pk_bf16_f32 v164, v164, v165
	v_cvt_pk_bf16_f32 v165, v166, v167
	global_store_dwordx2 v[62:63], v[164:165], off offset:512
	v_cvt_pk_bf16_f32 v168, v168, v169
	v_cvt_pk_bf16_f32 v169, v170, v171
	global_store_dwordx2 v[62:63], v[168:169], off offset:1024
	v_cvt_pk_bf16_f32 v172, v172, v173
	v_cvt_pk_bf16_f32 v173, v174, v175
	global_store_dwordx2 v[62:63], v[172:173], off offset:1536
	v_cvt_pk_bf16_f32 v176, v176, v177
	v_cvt_pk_bf16_f32 v177, v178, v179
	global_store_dwordx2 v[62:63], v[176:177], off offset:2048
	v_cvt_pk_bf16_f32 v180, v180, v181
	v_cvt_pk_bf16_f32 v181, v182, v183
	global_store_dwordx2 v[62:63], v[180:181], off offset:2560
	v_cvt_pk_bf16_f32 v184, v184, v185
	v_cvt_pk_bf16_f32 v185, v186, v187
	global_store_dwordx2 v[62:63], v[184:185], off offset:3072
	v_cvt_pk_bf16_f32 v188, v188, v189
	v_cvt_pk_bf16_f32 v189, v190, v191
	global_store_dwordx2 v[62:63], v[188:189], off offset:3584
	ds_bpermute_b32 v12, v40, v8
	ds_bpermute_b32 v13, v40, v9
	ds_bpermute_b32 v14, v40, v10
	ds_bpermute_b32 v15, v40, v11
	s_waitcnt lgkmcnt(0)
	v_add_f32_e32 v8, v8, v12
	v_add_f32_e32 v9, v9, v13
	v_add_f32_e32 v10, v10, v14
	v_add_f32_e32 v11, v11, v15
	ds_bpermute_b32 v12, v41, v8
	ds_bpermute_b32 v13, v41, v9
	ds_bpermute_b32 v14, v41, v10
	ds_bpermute_b32 v15, v41, v11
	s_waitcnt lgkmcnt(0)
	v_add_f32_e32 v8, v8, v12
	v_add_f32_e32 v9, v9, v13
	v_add_f32_e32 v10, v10, v14
	v_add_f32_e32 v11, v11, v15
	ds_bpermute_b32 v12, v42, v8
	ds_bpermute_b32 v13, v42, v9
	ds_bpermute_b32 v14, v42, v10
	ds_bpermute_b32 v15, v42, v11
	s_waitcnt lgkmcnt(0)
	v_add_f32_e32 v8, v8, v12
	v_add_f32_e32 v9, v9, v13
	v_add_f32_e32 v10, v10, v14
	v_add_f32_e32 v11, v11, v15
	ds_bpermute_b32 v12, v43, v8
	ds_bpermute_b32 v13, v43, v9
	ds_bpermute_b32 v14, v43, v10
	ds_bpermute_b32 v15, v43, v11
	s_waitcnt lgkmcnt(0)
	v_add_f32_e32 v8, v8, v12
	v_add_f32_e32 v9, v9, v13
	v_add_f32_e32 v10, v10, v14
	v_add_f32_e32 v11, v11, v15
	ds_bpermute_b32 v12, v44, v8
	ds_bpermute_b32 v13, v44, v9
	ds_bpermute_b32 v14, v44, v10
	ds_bpermute_b32 v15, v44, v11
	s_waitcnt lgkmcnt(0)
	v_add_f32_e32 v8, v8, v12
	v_add_f32_e32 v9, v9, v13
	v_add_f32_e32 v10, v10, v14
	v_add_f32_e32 v11, v11, v15
	ds_bpermute_b32 v12, v45, v8
	ds_bpermute_b32 v13, v45, v9
	ds_bpermute_b32 v14, v45, v10
	ds_bpermute_b32 v15, v45, v11
	s_waitcnt lgkmcnt(0)
	v_add_f32_e32 v8, v8, v12
	v_add_f32_e32 v9, v9, v13
	v_add_f32_e32 v10, v10, v14
	v_add_f32_e32 v11, v11, v15
	v_cndmask_b32_e64 v16, 0, v8, s[6:7]
	v_cndmask_b32_e64 v17, 0, v9, s[6:7]
	v_cndmask_b32_e64 v18, 0, v10, s[6:7]
	v_cndmask_b32_e64 v19, 0, v11, s[6:7]
	s_and_saveexec_b64 s[0:1], s[4:5]
	global_store_dword v[192:193], v16, off
	global_store_dword v[194:195], v17, off
	global_store_dword v[196:197], v18, off
	global_store_dword v[198:199], v19, off
	s_or_b64 exec, exec, s[0:1]
	s_branch .LBB0_457
